# W_mla weight conversion: branch-free, all loads in one round trip (was 16 predicated blocks with a full wait each)
# baseline (speedup 1.0000x reference)
; __device__ __forceinline__ unsigned cvt_pk(float lo, float hi) { f32x2_t v = {lo, hi}; bf16x2_t b = __builtin_convertvector(v, bf16x2_t); return __builtin_bit_cast(unsigned, b); }
; __device__ __forceinline__ void phase_convert(const Ctx& a, int l, LAS unsigned char* lds) {
;     ...
;             int n = ch % MR, kc = (ch / MR) * 8;
;             float v[8];
; #pragma unroll
;             for (int e = 0; e < 8; ++e) {
;                 const int k = kc + e;
;                 const int kq_ = k < 256 ? k : 255, nq_ = n < 768 ? n : 767, kk_ = k >= 256 ? k - 256 : 0, nk_ = n >= 768 ? n - 768 : 0;
;                 const float xq = gq[kq_] * wuq[(size_t)kq_ * 768 + nq_], xk = gkv[kk_] * wukv[(size_t)kk_ * 1024 + nk_];
;                 v[e] = (n < 768) ? (k < 256 ? xq : 0.f) : (k >= 256 ? xk : 0.f);
;             }
;             u32x4 w; w[0] = cvt_pk(v[0], v[1]); w[1] = cvt_pk(v[2], v[3]); w[2] = cvt_pk(v[4], v[5]); w[3] = cvt_pk(v[6], v[7]);
;             *(u32x4*)(dst + (size_t)n * 384 + kc) = w;
.LBB0_756:
	s_mov_b32 s30, 0x92492493
	v_mul_hi_i32 v13, v11, s30
	v_add_u32_e32 v13, v13, v11
	v_lshrrev_b32_e32 v14, 31, v13
	v_ashrrev_i32_e32 v13, 10, v13
	v_add_u32_e32 v14, v13, v14
	v_mul_i32_i24_e32 v13, 0x700, v14
	v_sub_u32_e32 v144, v11, v13
	s_movk_i32 s30, 0x2ff
	v_lshlrev_b32_e32 v14, 3, v14
	v_cmp_lt_i32_e64 s[36:37], s30, v144
	v_lshl_add_u64 v[16:17], v[144:145], 2, v[8:9]
	s_mov_b32 s8, 0xdfff
	v_cmp_lt_i32_e32 vcc, s8, v11
	s_xor_b64 s[38:39], vcc, s[36:37]
	s_not_b64 s[38:39], s[38:39]
	v_subrev_u32_e32 v30, 0x100, v14
	v_cndmask_b32_e64 v30, v14, v30, s[36:37]
	v_cndmask_b32_e64 v30, 0, v30, s[38:39]
	v_subrev_u32_e32 v31, 0x300, v144
	v_cndmask_b32_e64 v31, v144, v31, s[36:37]
	v_lshlrev_b32_e32 v31, 2, v31
	v_cndmask_b32_e64 v32, v6, v8, s[36:37]
	v_cndmask_b32_e64 v33, v7, v9, s[36:37]
	v_mov_b32_e32 v34, 0xc00
	v_mov_b32_e32 v35, 0x1000
	v_cndmask_b32_e64 v34, v34, v35, s[36:37]
	v_mad_u64_u32 v[36:37], s[40:41], v30, v34, v[32:33]
	v_add_co_u32_e32 v36, vcc, v36, v31
	v_addc_co_u32_e32 v37, vcc, 0, v37, vcc
	v_cndmask_b32_e64 v38, v2, v4, s[36:37]
	v_cndmask_b32_e64 v39, v3, v5, s[36:37]
	v_lshlrev_b32_e32 v40, 2, v30
	v_mov_b32_e32 v41, 0
	v_lshl_add_u64 v[38:39], v[40:41], 0, v[38:39]
	global_load_dwordx4 v[42:45], v[38:39], off
	global_load_dwordx4 v[46:49], v[38:39], off offset:16
	global_load_dword v50, v[36:37], off
	v_add_co_u32_e32 v36, vcc, v36, v34
	v_addc_co_u32_e32 v37, vcc, 0, v37, vcc
	global_load_dword v51, v[36:37], off
	v_add_co_u32_e32 v36, vcc, v36, v34
	v_addc_co_u32_e32 v37, vcc, 0, v37, vcc
	global_load_dword v52, v[36:37], off
	v_add_co_u32_e32 v36, vcc, v36, v34
	v_addc_co_u32_e32 v37, vcc, 0, v37, vcc
	global_load_dword v53, v[36:37], off
	v_add_co_u32_e32 v36, vcc, v36, v34
	v_addc_co_u32_e32 v37, vcc, 0, v37, vcc
	global_load_dword v54, v[36:37], off
	v_add_co_u32_e32 v36, vcc, v36, v34
	v_addc_co_u32_e32 v37, vcc, 0, v37, vcc
	global_load_dword v55, v[36:37], off
	v_add_co_u32_e32 v36, vcc, v36, v34
	v_addc_co_u32_e32 v37, vcc, 0, v37, vcc
	global_load_dword v56, v[36:37], off
	v_add_co_u32_e32 v36, vcc, v36, v34
	v_addc_co_u32_e32 v37, vcc, 0, v37, vcc
	global_load_dword v57, v[36:37], off
	s_waitcnt vmcnt(0)
	v_mul_f32_e32 v15, v42, v50
	v_cndmask_b32_e64 v15, 0, v15, s[38:39]
	v_mul_f32_e32 v20, v43, v51
	v_cndmask_b32_e64 v20, 0, v20, s[38:39]
	v_mul_f32_e32 v21, v44, v52
	v_cndmask_b32_e64 v21, 0, v21, s[38:39]
	v_mul_f32_e32 v22, v45, v53
	v_cndmask_b32_e64 v22, 0, v22, s[38:39]
	v_mul_f32_e32 v23, v46, v54
	v_cndmask_b32_e64 v23, 0, v23, s[38:39]
	v_mul_f32_e32 v24, v47, v55
	v_cndmask_b32_e64 v24, 0, v24, s[38:39]
	v_mul_f32_e32 v25, v48, v56
	v_cndmask_b32_e64 v25, 0, v25, s[38:39]
	v_mul_f32_e32 v27, v49, v57
	v_cndmask_b32_e64 v27, 0, v27, s[38:39]
	s_mov_b64 s[36:37], exec
	s_branch .LBB0_755
